# stack21 + counted LDS waits in the B_MIX MFMA loop: the four Ws-fragment reads of a k-step issued together into separate registers, lgkmcnt(3..0) before each MFMA
# speedup vs baseline: 1.0060x; 1.0060x over previous
.LBB0_150:
	v_add_u32_e32 v74, 0xffffdc00, v0
	v_add_u32_e32 v97, s2, v94
	v_add_u32_e32 v75, 0xffffe500, v0
	v_add_u32_e32 v244, 0x12100, v97
	ds_read_b64_tr_b16 v[70:71], v74
	ds_read_b64_tr_b16 v[72:73], v75
	ds_read_b128 v[74:77], v244
	ds_read_b128 v[232:235], v244 offset:8704
	ds_read_b128 v[236:239], v244 offset:17408
	ds_read_b128 v[240:243], v244 offset:26112
	s_add_i32 s2, s2, 64
	s_waitcnt lgkmcnt(3)
	v_mfma_f32_32x32x16_bf16 v[50:65], v[70:73], v[74:77], v[50:65]
	s_waitcnt lgkmcnt(2)
	v_mfma_f32_32x32x16_bf16 v[34:49], v[70:73], v[232:235], v[34:49]
	s_waitcnt lgkmcnt(1)
	v_mfma_f32_32x32x16_bf16 v[18:33], v[70:73], v[236:239], v[18:33]
	s_waitcnt lgkmcnt(0)
	v_mfma_f32_32x32x16_bf16 v[2:17], v[70:73], v[240:243], v[2:17]
	v_add_u32_e32 v74, 0x900, v0
	ds_read_b64_tr_b16 v[70:71], v0
	ds_read_b64_tr_b16 v[72:73], v74
	ds_read_b128 v[74:77], v244 offset:32
	ds_read_b128 v[232:235], v244 offset:8736
	ds_read_b128 v[236:239], v244 offset:17440
	ds_read_b128 v[240:243], v244 offset:26144
	v_add_u32_e32 v0, 0x4800, v0
	s_cmp_eq_u32 s2, 0
	s_waitcnt lgkmcnt(3)
	v_mfma_f32_32x32x16_bf16 v[50:65], v[70:73], v[74:77], v[50:65]
	s_waitcnt lgkmcnt(2)
	v_mfma_f32_32x32x16_bf16 v[34:49], v[70:73], v[232:235], v[34:49]
	s_waitcnt lgkmcnt(1)
	v_mfma_f32_32x32x16_bf16 v[18:33], v[70:73], v[236:239], v[18:33]
	s_waitcnt lgkmcnt(0)
	v_mfma_f32_32x32x16_bf16 v[2:17], v[70:73], v[240:243], v[2:17]
	s_cbranch_scc0 .LBB0_150
	s_waitcnt vmcnt(0)
	s_lshl_b32 s80, s1, 1
	s_lshl_b32 s56, s0, 12
	s_add_i32 s56, s56, s80
	s_mov_b32 s57, 0
	s_mov_b64 s[58:59], 0x10000
	v_lshl_add_u64 v[72:73], v[138:139], 0, s[56:57]
	ds_write_b128 v149, v[160:163]
	ds_write_b128 v149, v[164:167] offset:1280
	ds_write_b128 v149, v[168:171] offset:2560
	ds_write_b128 v149, v[172:175] offset:3840
	s_waitcnt lgkmcnt(0)
	ds_read_b64 v[200:201], v141
	ds_read_b64 v[202:203], v141 offset:16
	ds_read_b64 v[204:205], v141 offset:32
	ds_read_b64 v[206:207], v141 offset:48
	ds_read_b64 v[208:209], v141 offset:2560
	ds_read_b64 v[210:211], v141 offset:2576
	ds_read_b64 v[212:213], v141 offset:2592
	ds_read_b64 v[214:215], v141 offset:2608
	v_add_f32_e32 v50, v50, v192
	v_add_f32_e32 v51, v51, v192
	v_add_f32_e32 v52, v52, v192
	v_add_f32_e32 v53, v53, v192
	v_add_f32_e32 v54, v54, v192
	v_add_f32_e32 v55, v55, v192
	v_add_f32_e32 v56, v56, v192
	v_add_f32_e32 v57, v57, v192
	v_add_f32_e32 v58, v58, v192
	v_add_f32_e32 v59, v59, v192
	v_add_f32_e32 v60, v60, v192
	v_add_f32_e32 v61, v61, v192
	v_add_f32_e32 v62, v62, v192
	v_add_f32_e32 v63, v63, v192
	v_add_f32_e32 v64, v64, v192
	v_add_f32_e32 v65, v65, v192
	v_add_f32_e32 v34, v34, v193
	v_add_f32_e32 v35, v35, v193
	v_add_f32_e32 v36, v36, v193
	v_add_f32_e32 v37, v37, v193
	v_add_f32_e32 v38, v38, v193
	v_add_f32_e32 v39, v39, v193
	v_add_f32_e32 v40, v40, v193
	v_add_f32_e32 v41, v41, v193
	v_add_f32_e32 v42, v42, v193
	v_add_f32_e32 v43, v43, v193
	v_add_f32_e32 v44, v44, v193
	v_add_f32_e32 v45, v45, v193
	v_add_f32_e32 v46, v46, v193
	v_add_f32_e32 v47, v47, v193
	v_add_f32_e32 v48, v48, v193
	v_add_f32_e32 v49, v49, v193
	s_waitcnt lgkmcnt(0)
	v_lshlrev_b32_e32 v216, 16, v200
	v_and_b32_e32 v217, 0xffff0000, v200
	v_lshlrev_b32_e32 v218, 16, v201
	v_and_b32_e32 v219, 0xffff0000, v201
	v_mul_f32_e32 v50, v50, v216
	v_mul_f32_e32 v51, v51, v217
	v_mul_f32_e32 v52, v52, v218
	v_mul_f32_e32 v53, v53, v219
	v_cvt_pk_bf16_f32 v200, v50, v51
	v_cvt_pk_bf16_f32 v201, v52, v53
	ds_write_b64 v141, v[200:201]
	v_lshlrev_b32_e32 v216, 16, v202
	v_and_b32_e32 v217, 0xffff0000, v202
	v_lshlrev_b32_e32 v218, 16, v203
	v_and_b32_e32 v219, 0xffff0000, v203
	v_mul_f32_e32 v54, v54, v216
	v_mul_f32_e32 v55, v55, v217
	v_mul_f32_e32 v56, v56, v218
	v_mul_f32_e32 v57, v57, v219
	v_cvt_pk_bf16_f32 v202, v54, v55
	v_cvt_pk_bf16_f32 v203, v56, v57
	ds_write_b64 v141, v[202:203] offset:16
	v_lshlrev_b32_e32 v216, 16, v204
	v_and_b32_e32 v217, 0xffff0000, v204
	v_lshlrev_b32_e32 v218, 16, v205
	v_and_b32_e32 v219, 0xffff0000, v205
	v_mul_f32_e32 v58, v58, v216
	v_mul_f32_e32 v59, v59, v217
	v_mul_f32_e32 v60, v60, v218
	v_mul_f32_e32 v61, v61, v219
	v_cvt_pk_bf16_f32 v204, v58, v59
	v_cvt_pk_bf16_f32 v205, v60, v61
	ds_write_b64 v141, v[204:205] offset:32
	v_lshlrev_b32_e32 v216, 16, v206
	v_and_b32_e32 v217, 0xffff0000, v206
	v_lshlrev_b32_e32 v218, 16, v207
	v_and_b32_e32 v219, 0xffff0000, v207
	v_mul_f32_e32 v62, v62, v216
	v_mul_f32_e32 v63, v63, v217
	v_mul_f32_e32 v64, v64, v218
	v_mul_f32_e32 v65, v65, v219
	v_cvt_pk_bf16_f32 v206, v62, v63
	v_cvt_pk_bf16_f32 v207, v64, v65
	ds_write_b64 v141, v[206:207] offset:48
	v_lshlrev_b32_e32 v216, 16, v208
	v_and_b32_e32 v217, 0xffff0000, v208
	v_lshlrev_b32_e32 v218, 16, v209
	v_and_b32_e32 v219, 0xffff0000, v209
	v_mul_f32_e32 v34, v34, v216
	v_mul_f32_e32 v35, v35, v217
	v_mul_f32_e32 v36, v36, v218
	v_mul_f32_e32 v37, v37, v219
	v_cvt_pk_bf16_f32 v208, v34, v35
	v_cvt_pk_bf16_f32 v209, v36, v37
	ds_write_b64 v141, v[208:209] offset:2560
	v_lshlrev_b32_e32 v216, 16, v210
	v_and_b32_e32 v217, 0xffff0000, v210
	v_lshlrev_b32_e32 v218, 16, v211
	v_and_b32_e32 v219, 0xffff0000, v211
	v_mul_f32_e32 v38, v38, v216
	v_mul_f32_e32 v39, v39, v217
	v_mul_f32_e32 v40, v40, v218
	v_mul_f32_e32 v41, v41, v219
	v_cvt_pk_bf16_f32 v210, v38, v39
	v_cvt_pk_bf16_f32 v211, v40, v41
	ds_write_b64 v141, v[210:211] offset:2576
	v_lshlrev_b32_e32 v216, 16, v212
	v_and_b32_e32 v217, 0xffff0000, v212
	v_lshlrev_b32_e32 v218, 16, v213
	v_and_b32_e32 v219, 0xffff0000, v213
	v_mul_f32_e32 v42, v42, v216
	v_mul_f32_e32 v43, v43, v217
	v_mul_f32_e32 v44, v44, v218
	v_mul_f32_e32 v45, v45, v219
	v_cvt_pk_bf16_f32 v212, v42, v43
	v_cvt_pk_bf16_f32 v213, v44, v45
	ds_write_b64 v141, v[212:213] offset:2592
	v_lshlrev_b32_e32 v216, 16, v214
	v_and_b32_e32 v217, 0xffff0000, v214
	v_lshlrev_b32_e32 v218, 16, v215
	v_and_b32_e32 v219, 0xffff0000, v215
	v_mul_f32_e32 v46, v46, v216
	v_mul_f32_e32 v47, v47, v217
	v_mul_f32_e32 v48, v48, v218
	v_mul_f32_e32 v49, v49, v219
	v_cvt_pk_bf16_f32 v214, v46, v47
	v_cvt_pk_bf16_f32 v215, v48, v49
	ds_write_b64 v141, v[214:215] offset:2608
	s_waitcnt lgkmcnt(0)
	ds_read_b128 v[160:163], v140
	ds_read_b128 v[164:167], v140 offset:1280
	ds_read_b128 v[168:171], v140 offset:2560
	ds_read_b128 v[172:175], v140 offset:3840
	s_waitcnt lgkmcnt(3)
	global_store_dwordx4 v[72:73], v[160:163], off
	v_lshl_add_u64 v[72:73], v[72:73], 0, s[58:59]
	s_waitcnt lgkmcnt(2)
	global_store_dwordx4 v[72:73], v[164:167], off
	v_lshl_add_u64 v[72:73], v[72:73], 0, s[58:59]
	s_waitcnt lgkmcnt(1)
	global_store_dwordx4 v[72:73], v[168:171], off
	v_lshl_add_u64 v[72:73], v[72:73], 0, s[58:59]
	s_waitcnt lgkmcnt(0)
	global_store_dwordx4 v[72:73], v[172:175], off
	v_lshl_add_u64 v[72:73], v[72:73], 0, s[58:59]
	ds_write_b128 v149, v[176:179]
	ds_write_b128 v149, v[180:183] offset:1280
	ds_write_b128 v149, v[184:187] offset:2560
	ds_write_b128 v149, v[188:191] offset:3840
	s_waitcnt lgkmcnt(0)
	ds_read_b64 v[200:201], v141
	ds_read_b64 v[202:203], v141 offset:16
	ds_read_b64 v[204:205], v141 offset:32
	ds_read_b64 v[206:207], v141 offset:48
	ds_read_b64 v[208:209], v141 offset:2560
	ds_read_b64 v[210:211], v141 offset:2576
	ds_read_b64 v[212:213], v141 offset:2592
	ds_read_b64 v[214:215], v141 offset:2608
	v_add_f32_e32 v18, v18, v194
	v_add_f32_e32 v19, v19, v194
	v_add_f32_e32 v20, v20, v194
	v_add_f32_e32 v21, v21, v194
	v_add_f32_e32 v22, v22, v194
	v_add_f32_e32 v23, v23, v194
	v_add_f32_e32 v24, v24, v194
	v_add_f32_e32 v25, v25, v194
	v_add_f32_e32 v26, v26, v194
	v_add_f32_e32 v27, v27, v194
	v_add_f32_e32 v28, v28, v194
	v_add_f32_e32 v29, v29, v194
	v_add_f32_e32 v30, v30, v194
	v_add_f32_e32 v31, v31, v194
	v_add_f32_e32 v32, v32, v194
	v_add_f32_e32 v33, v33, v194
	v_add_f32_e32 v2, v2, v195
	v_add_f32_e32 v3, v3, v195
	v_add_f32_e32 v4, v4, v195
	v_add_f32_e32 v5, v5, v195
	v_add_f32_e32 v6, v6, v195
	v_add_f32_e32 v7, v7, v195
	v_add_f32_e32 v8, v8, v195
	v_add_f32_e32 v9, v9, v195
	v_add_f32_e32 v10, v10, v195
	v_add_f32_e32 v11, v11, v195
	v_add_f32_e32 v12, v12, v195
	v_add_f32_e32 v13, v13, v195
	v_add_f32_e32 v14, v14, v195
	v_add_f32_e32 v15, v15, v195
	v_add_f32_e32 v16, v16, v195
	v_add_f32_e32 v17, v17, v195
	s_waitcnt lgkmcnt(0)
	v_lshlrev_b32_e32 v216, 16, v200
	v_and_b32_e32 v217, 0xffff0000, v200
	v_lshlrev_b32_e32 v218, 16, v201
	v_and_b32_e32 v219, 0xffff0000, v201
	v_mul_f32_e32 v18, v18, v216
	v_mul_f32_e32 v19, v19, v217
	v_mul_f32_e32 v20, v20, v218
	v_mul_f32_e32 v21, v21, v219
	v_cvt_pk_bf16_f32 v200, v18, v19
	v_cvt_pk_bf16_f32 v201, v20, v21
	ds_write_b64 v141, v[200:201]
	v_lshlrev_b32_e32 v216, 16, v202
	v_and_b32_e32 v217, 0xffff0000, v202
	v_lshlrev_b32_e32 v218, 16, v203
	v_and_b32_e32 v219, 0xffff0000, v203
	v_mul_f32_e32 v22, v22, v216
	v_mul_f32_e32 v23, v23, v217
	v_mul_f32_e32 v24, v24, v218
	v_mul_f32_e32 v25, v25, v219
	v_cvt_pk_bf16_f32 v202, v22, v23
	v_cvt_pk_bf16_f32 v203, v24, v25
	ds_write_b64 v141, v[202:203] offset:16
	v_lshlrev_b32_e32 v216, 16, v204
	v_and_b32_e32 v217, 0xffff0000, v204
	v_lshlrev_b32_e32 v218, 16, v205
	v_and_b32_e32 v219, 0xffff0000, v205
	v_mul_f32_e32 v26, v26, v216
	v_mul_f32_e32 v27, v27, v217
	v_mul_f32_e32 v28, v28, v218
	v_mul_f32_e32 v29, v29, v219
	v_cvt_pk_bf16_f32 v204, v26, v27
	v_cvt_pk_bf16_f32 v205, v28, v29
	ds_write_b64 v141, v[204:205] offset:32
	v_lshlrev_b32_e32 v216, 16, v206
	v_and_b32_e32 v217, 0xffff0000, v206
	v_lshlrev_b32_e32 v218, 16, v207
	v_and_b32_e32 v219, 0xffff0000, v207
	v_mul_f32_e32 v30, v30, v216
	v_mul_f32_e32 v31, v31, v217
	v_mul_f32_e32 v32, v32, v218
	v_mul_f32_e32 v33, v33, v219
	v_cvt_pk_bf16_f32 v206, v30, v31
	v_cvt_pk_bf16_f32 v207, v32, v33
	ds_write_b64 v141, v[206:207] offset:48
	v_lshlrev_b32_e32 v216, 16, v208
	v_and_b32_e32 v217, 0xffff0000, v208
	v_lshlrev_b32_e32 v218, 16, v209
	v_and_b32_e32 v219, 0xffff0000, v209
	v_mul_f32_e32 v2, v2, v216
	v_mul_f32_e32 v3, v3, v217
	v_mul_f32_e32 v4, v4, v218
	v_mul_f32_e32 v5, v5, v219
	v_cvt_pk_bf16_f32 v208, v2, v3
	v_cvt_pk_bf16_f32 v209, v4, v5
	ds_write_b64 v141, v[208:209] offset:2560
	v_lshlrev_b32_e32 v216, 16, v210
	v_and_b32_e32 v217, 0xffff0000, v210
	v_lshlrev_b32_e32 v218, 16, v211
	v_and_b32_e32 v219, 0xffff0000, v211
	v_mul_f32_e32 v6, v6, v216
	v_mul_f32_e32 v7, v7, v217
	v_mul_f32_e32 v8, v8, v218
	v_mul_f32_e32 v9, v9, v219
	v_cvt_pk_bf16_f32 v210, v6, v7
	v_cvt_pk_bf16_f32 v211, v8, v9
	ds_write_b64 v141, v[210:211] offset:2576
	v_lshlrev_b32_e32 v216, 16, v212
	v_and_b32_e32 v217, 0xffff0000, v212
	v_lshlrev_b32_e32 v218, 16, v213
	v_and_b32_e32 v219, 0xffff0000, v213
	v_mul_f32_e32 v10, v10, v216
	v_mul_f32_e32 v11, v11, v217
	v_mul_f32_e32 v12, v12, v218
	v_mul_f32_e32 v13, v13, v219
	v_cvt_pk_bf16_f32 v212, v10, v11
	v_cvt_pk_bf16_f32 v213, v12, v13
	ds_write_b64 v141, v[212:213] offset:2592
	v_lshlrev_b32_e32 v216, 16, v214
	v_and_b32_e32 v217, 0xffff0000, v214
	v_lshlrev_b32_e32 v218, 16, v215
	v_and_b32_e32 v219, 0xffff0000, v215
	v_mul_f32_e32 v14, v14, v216
	v_mul_f32_e32 v15, v15, v217
	v_mul_f32_e32 v16, v16, v218
	v_mul_f32_e32 v17, v17, v219
	v_cvt_pk_bf16_f32 v214, v14, v15
	v_cvt_pk_bf16_f32 v215, v16, v17
	ds_write_b64 v141, v[214:215] offset:2608
	s_waitcnt lgkmcnt(0)
	ds_read_b128 v[176:179], v140
	ds_read_b128 v[180:183], v140 offset:1280
	ds_read_b128 v[184:187], v140 offset:2560
	ds_read_b128 v[188:191], v140 offset:3840
	s_waitcnt lgkmcnt(3)
	global_store_dwordx4 v[72:73], v[176:179], off
	v_lshl_add_u64 v[72:73], v[72:73], 0, s[58:59]
	s_waitcnt lgkmcnt(2)
	global_store_dwordx4 v[72:73], v[180:183], off
	v_lshl_add_u64 v[72:73], v[72:73], 0, s[58:59]
	s_waitcnt lgkmcnt(1)
	global_store_dwordx4 v[72:73], v[184:187], off
	v_lshl_add_u64 v[72:73], v[72:73], 0, s[58:59]
	s_waitcnt lgkmcnt(0)
	global_store_dwordx4 v[72:73], v[188:191], off
	v_readlane_b32 s52, v249, 13
	v_readlane_b32 s53, v249, 14
	v_readlane_b32 s54, v249, 15
	v_readlane_b32 s55, v249, 16
	v_readlane_b32 s56, v249, 17
	v_readlane_b32 s57, v249, 18
	v_readlane_b32 s58, v249, 19
	v_readlane_b32 s59, v249, 20
	v_readlane_b32 s62, v249, 23
	v_readlane_b32 s63, v249, 24
	v_readlane_b32 s64, v249, 25
	v_readlane_b32 s65, v249, 26
	v_readlane_b32 s66, v249, 27
	v_readlane_b32 s67, v249, 28
	v_readlane_b32 s23, v249, 41
	v_readlane_b32 s60, v248, 31
	v_readlane_b32 s61, v248, 32
	s_add_i32 s12, s12, s34
	s_cmpk_gt_i32 s12, 0x3ff
	s_cbranch_scc0 .LBB0_144
